# attention A loop: common (constant-bias) path made branch-free - scalar select for the bias constant, tuple update / gather / pending-rescale blocks moved out of line, single taken back-edge
# speedup vs baseline: 1.0051x; 1.0051x over previous
; __device__ __forceinline__ void attn_unit_a(FLAS unsigned char* lds, const Unit u) {
;     ...
;         if (pend) {
; #pragma unroll
;             for (int d = 0; d < NDB; ++d) o[d] = o[d] * fpend;
;             pend = false; }
.Lpend_e:
	v_pk_mul_f32 v[62:63], v[226:227], v[62:63] op_sel_hi:[0,1]
	v_pk_mul_f32 v[60:61], v[226:227], v[60:61] op_sel_hi:[0,1]
	v_pk_mul_f32 v[58:59], v[226:227], v[58:59] op_sel_hi:[0,1]
	v_pk_mul_f32 v[56:57], v[226:227], v[56:57] op_sel_hi:[0,1]
	v_pk_mul_f32 v[54:55], v[226:227], v[54:55] op_sel_hi:[0,1]
	v_pk_mul_f32 v[52:53], v[226:227], v[52:53] op_sel_hi:[0,1]
	v_pk_mul_f32 v[50:51], v[226:227], v[50:51] op_sel_hi:[0,1]
	v_pk_mul_f32 v[48:49], v[226:227], v[48:49] op_sel_hi:[0,1]
	v_pk_mul_f32 v[46:47], v[226:227], v[46:47] op_sel_hi:[0,1]
	v_pk_mul_f32 v[44:45], v[226:227], v[44:45] op_sel_hi:[0,1]
	v_pk_mul_f32 v[42:43], v[226:227], v[42:43] op_sel_hi:[0,1]
	v_pk_mul_f32 v[40:41], v[226:227], v[40:41] op_sel_hi:[0,1]
	v_pk_mul_f32 v[38:39], v[226:227], v[38:39] op_sel_hi:[0,1]
	v_pk_mul_f32 v[36:37], v[226:227], v[36:37] op_sel_hi:[0,1]
	v_pk_mul_f32 v[34:35], v[226:227], v[34:35] op_sel_hi:[0,1]
	v_pk_mul_f32 v[32:33], v[226:227], v[32:33] op_sel_hi:[0,1]
	v_pk_mul_f32 v[30:31], v[226:227], v[30:31] op_sel_hi:[0,1]
	v_pk_mul_f32 v[28:29], v[226:227], v[28:29] op_sel_hi:[0,1]
	v_pk_mul_f32 v[26:27], v[226:227], v[26:27] op_sel_hi:[0,1]
	v_pk_mul_f32 v[24:25], v[226:227], v[24:25] op_sel_hi:[0,1]
	v_pk_mul_f32 v[22:23], v[226:227], v[22:23] op_sel_hi:[0,1]
	v_pk_mul_f32 v[20:21], v[226:227], v[20:21] op_sel_hi:[0,1]
	v_pk_mul_f32 v[18:19], v[226:227], v[18:19] op_sel_hi:[0,1]
	v_pk_mul_f32 v[16:17], v[226:227], v[16:17] op_sel_hi:[0,1]
	v_pk_mul_f32 v[14:15], v[226:227], v[14:15] op_sel_hi:[0,1]
	v_pk_mul_f32 v[12:13], v[226:227], v[12:13] op_sel_hi:[0,1]
	v_pk_mul_f32 v[10:11], v[226:227], v[10:11] op_sel_hi:[0,1]
	v_pk_mul_f32 v[8:9], v[226:227], v[8:9] op_sel_hi:[0,1]
	v_pk_mul_f32 v[6:7], v[226:227], v[6:7] op_sel_hi:[0,1]
	v_pk_mul_f32 v[4:5], v[226:227], v[4:5] op_sel_hi:[0,1]
	v_pk_mul_f32 v[2:3], v[226:227], v[2:3] op_sel_hi:[0,1]
	v_pk_mul_f32 v[0:1], v[226:227], v[0:1] op_sel_hi:[0,1]
	s_branch .LBB0_458
.Lz_upd_e:
	v_mov_b32_e32 v144, v142
	v_mov_b32_e32 v145, v142
	v_mov_b32_e32 v146, v142
	v_mov_b32_e32 v147, v142
	v_mov_b32_e32 v148, v142
	v_mov_b32_e32 v149, v142
	v_mov_b32_e32 v150, v142
	v_mov_b32_e32 v151, v142
	v_mov_b32_e32 v152, v142
	v_mov_b32_e32 v153, v142
	v_mov_b32_e32 v154, v142
	v_mov_b32_e32 v155, v142
	v_mov_b32_e32 v156, v142
	v_mov_b32_e32 v157, v142
	v_mov_b32_e32 v158, v142
	v_mov_b32_e32 v159, v142
	s_nop 1
	s_branch .Lz_go_e
.Lgather_e:
	v_add_u32_e32 v76, s49, v210
	v_add_u32_e32 v64, 0x17600, v76
	v_add_u32_e32 v66, 0x17680, v76
	v_add_u32_e32 v67, 0x17608, v76
	v_add_u32_e32 v68, 0x17688, v76
	ds_read2_b32 v[64:65], v64 offset1:1
	ds_read2_b32 v[80:81], v66 offset1:1
	ds_read2_b32 v[66:67], v67 offset1:1
	ds_read2_b32 v[82:83], v68 offset1:1
	v_add_u32_e32 v68, 0x17620, v76
	v_add_u32_e32 v70, 0x176a0, v76
	v_add_u32_e32 v71, 0x17628, v76
	v_add_u32_e32 v72, 0x176a8, v76
	ds_read2_b32 v[68:69], v68 offset1:1
	ds_read2_b32 v[84:85], v70 offset1:1
	ds_read2_b32 v[70:71], v71 offset1:1
	ds_read2_b32 v[86:87], v72 offset1:1
	v_add_u32_e32 v72, 0x17640, v76
	v_add_u32_e32 v74, 0x176c0, v76
	v_add_u32_e32 v75, 0x17648, v76
	v_add_u32_e32 v77, 0x176c8, v76
	ds_read2_b32 v[72:73], v72 offset1:1
	ds_read2_b32 v[88:89], v74 offset1:1
	ds_read2_b32 v[74:75], v75 offset1:1
	ds_read2_b32 v[90:91], v77 offset1:1
	v_add_u32_e32 v77, 0x17660, v76
	v_add_u32_e32 v78, 0x176e0, v76
	v_add_u32_e32 v79, 0x17668, v76
	v_add_u32_e32 v94, 0x176e8, v76
	ds_read2_b32 v[76:77], v77 offset1:1
	ds_read2_b32 v[92:93], v78 offset1:1
	ds_read2_b32 v[78:79], v79 offset1:1
	ds_read2_b32 v[94:95], v94 offset1:1
	s_waitcnt lgkmcnt(0)
	v_sub_f32_e32 v64, v64, v211
	v_sub_f32_e32 v65, v65, v211
	v_sub_f32_e32 v66, v66, v211
	v_sub_f32_e32 v67, v67, v211
	v_sub_f32_e32 v68, v68, v211
	v_sub_f32_e32 v69, v69, v211
	v_sub_f32_e32 v70, v70, v211
	v_sub_f32_e32 v71, v71, v211
	v_sub_f32_e32 v72, v72, v211
	v_sub_f32_e32 v73, v73, v211
	v_sub_f32_e32 v74, v74, v211
	v_sub_f32_e32 v75, v75, v211
	v_sub_f32_e32 v76, v76, v211
	v_sub_f32_e32 v77, v77, v211
	v_sub_f32_e32 v78, v78, v211
	v_sub_f32_e32 v79, v79, v211
	v_sub_f32_e32 v80, v80, v211
	v_sub_f32_e32 v81, v81, v211
	v_sub_f32_e32 v82, v82, v211
	v_sub_f32_e32 v83, v83, v211
	v_sub_f32_e32 v84, v84, v211
	v_sub_f32_e32 v85, v85, v211
	v_sub_f32_e32 v86, v86, v211
	v_sub_f32_e32 v87, v87, v211
	v_sub_f32_e32 v88, v88, v211
	v_sub_f32_e32 v89, v89, v211
	v_sub_f32_e32 v90, v90, v211
	v_sub_f32_e32 v91, v91, v211
	v_sub_f32_e32 v92, v92, v211
	v_sub_f32_e32 v93, v93, v211
	v_sub_f32_e32 v94, v94, v211
	v_sub_f32_e32 v95, v95, v211
	s_nop 1
	v_mfma_f32_32x32x16_bf16 v[64:79], v[204:207], v[160:163], v[64:79]
	v_exp_f32_e32 v112, v112
	v_exp_f32_e32 v113, v113
	v_add_f32_e32 v212, v110, v212
	v_add_f32_e32 v212, v111, v212
	v_mfma_f32_32x32x16_bf16 v[80:95], v[200:203], v[160:163], v[80:95]
	v_exp_f32_e32 v114, v114
	v_exp_f32_e32 v115, v115
	s_branch .Lk2_e

; #define FA_SB() __builtin_amdgcn_sched_barrier(0)
; #define FA_EXP2(J, PX, R) do { const float e0_ = __builtin_amdgcn_exp2f(PX[R]), e1_ = __builtin_amdgcn_exp2f(PX[(R) + 1]); ps += e0_; ps += e1_; PWN[(J) >> 2][(J) & 3] = cvtpk(e0_, e1_); } while (0)
; __device__ __forceinline__ void attn_unit_a(FLAS unsigned char* lds, const Unit u) {
;     ...
;         if (ziN) { pN0 = __builtin_amdgcn_mfma_f32_32x32x16_bf16(kf[0], qr[0], z16, 0, 0, 0); FA_EXP2(8, pC1, 0); FA_SB(); pN1 = __builtin_amdgcn_mfma_f32_32x32x16_bf16(kf[1], qr[0], z16, 0, 0, 0); }
;         else { pN0 = __builtin_amdgcn_mfma_f32_32x32x16_bf16(kf[0], qr[0], pN0, 0, 0, 0); FA_EXP2(8, pC1, 0); FA_SB(); pN1 = __builtin_amdgcn_mfma_f32_32x32x16_bf16(kf[1], qr[0], pN1, 0, 0, 0); }
.Lz_upd_o:
	v_mov_b32_e32 v144, v126
	v_mov_b32_e32 v145, v126
	v_mov_b32_e32 v146, v126
	v_mov_b32_e32 v147, v126
	v_mov_b32_e32 v148, v126
	v_mov_b32_e32 v149, v126
	v_mov_b32_e32 v150, v126
	v_mov_b32_e32 v151, v126
	v_mov_b32_e32 v152, v126
	v_mov_b32_e32 v153, v126
	v_mov_b32_e32 v154, v126
	v_mov_b32_e32 v155, v126
	v_mov_b32_e32 v156, v126
	v_mov_b32_e32 v157, v126
	v_mov_b32_e32 v158, v126
	v_mov_b32_e32 v159, v126
	s_nop 1
	s_branch .Lz_go_o
.Lgather_o:
	v_sub_u32_e32 v96, s12, v244
	v_lshl_add_u32 v108, v96, 2, v240
	v_add_u32_e32 v96, 0x1500, v108
	v_add_u32_e32 v98, 0x1580, v108
	v_add_u32_e32 v99, 0x1508, v108
	v_add_u32_e32 v100, 0x1588, v108
	ds_read2_b32 v[96:97], v96 offset1:1
	ds_read2_b32 v[112:113], v98 offset1:1
	ds_read2_b32 v[98:99], v99 offset1:1
	ds_read2_b32 v[114:115], v100 offset1:1
	v_add_u32_e32 v100, 0x1520, v108
	v_add_u32_e32 v102, 0x15a0, v108
	v_add_u32_e32 v103, 0x1528, v108
	v_add_u32_e32 v104, 0x15a8, v108
	ds_read2_b32 v[100:101], v100 offset1:1
	ds_read2_b32 v[116:117], v102 offset1:1
	ds_read2_b32 v[102:103], v103 offset1:1
	ds_read2_b32 v[118:119], v104 offset1:1
	v_add_u32_e32 v104, 0x1540, v108
	v_add_u32_e32 v106, 0x15c0, v108
	v_add_u32_e32 v107, 0x1548, v108
	v_add_u32_e32 v109, 0x15c8, v108
	ds_read2_b32 v[104:105], v104 offset1:1
	ds_read2_b32 v[120:121], v106 offset1:1
	ds_read2_b32 v[106:107], v107 offset1:1
	ds_read2_b32 v[122:123], v109 offset1:1
	v_add_u32_e32 v109, 0x1560, v108
	v_add_u32_e32 v110, 0x15e0, v108
	v_add_u32_e32 v111, 0x1568, v108
	v_add_u32_e32 v126, 0x15e8, v108
	ds_read2_b32 v[108:109], v109 offset1:1
	ds_read2_b32 v[124:125], v110 offset1:1
	ds_read2_b32 v[110:111], v111 offset1:1
	ds_read2_b32 v[126:127], v126 offset1:1
	s_waitcnt lgkmcnt(0)
	v_sub_f32_e32 v96, v96, v211
	v_sub_f32_e32 v97, v97, v211
	v_sub_f32_e32 v98, v98, v211
	v_sub_f32_e32 v99, v99, v211
	v_sub_f32_e32 v100, v100, v211
	v_sub_f32_e32 v101, v101, v211
	v_sub_f32_e32 v102, v102, v211
	v_sub_f32_e32 v103, v103, v211
	v_sub_f32_e32 v104, v104, v211
	v_sub_f32_e32 v105, v105, v211
	v_sub_f32_e32 v106, v106, v211
	v_sub_f32_e32 v107, v107, v211
	v_sub_f32_e32 v108, v108, v211
	v_sub_f32_e32 v109, v109, v211
	v_sub_f32_e32 v110, v110, v211
	v_sub_f32_e32 v111, v111, v211
	v_sub_f32_e32 v112, v112, v211
	v_sub_f32_e32 v113, v113, v211
	v_sub_f32_e32 v114, v114, v211
	v_sub_f32_e32 v115, v115, v211
	v_sub_f32_e32 v116, v116, v211
	v_sub_f32_e32 v117, v117, v211
	v_sub_f32_e32 v118, v118, v211
	v_sub_f32_e32 v119, v119, v211
	v_sub_f32_e32 v120, v120, v211
	v_sub_f32_e32 v121, v121, v211
	v_sub_f32_e32 v122, v122, v211
	v_sub_f32_e32 v123, v123, v211
	v_sub_f32_e32 v124, v124, v211
	v_sub_f32_e32 v125, v125, v211
	v_sub_f32_e32 v126, v126, v211
	v_sub_f32_e32 v127, v127, v211
	s_nop 1
	v_mfma_f32_32x32x16_bf16 v[96:111], v[200:203], v[160:163], v[96:111]
	v_exp_f32_e32 v80, v80
	v_exp_f32_e32 v81, v81
	v_add_f32_e32 v212, v78, v212
	v_add_f32_e32 v212, v79, v212
	v_mfma_f32_32x32x16_bf16 v[112:127], v[196:199], v[160:163], v[112:127]
	v_exp_f32_e32 v82, v82
	v_exp_f32_e32 v83, v83
	s_branch .Lk2_o

; #define FA_SB() __builtin_amdgcn_sched_barrier(0)
; #define FA_PVM(G) do { o[(G) & 3] = __builtin_amdgcn_mfma_f32_32x32x16_bf16(__builtin_bit_cast(bf16x8, vr[(G) % 3]), __builtin_bit_cast(bf16x8, PWC[(G) >> 2]), o[(G) & 3], 0, 0, 0); if ((G) + 3 < 16) vr[(G) % 3] = FA_VFRAG((G) + 3); } while (0)
; #define FA_EXP2(J, PX, R) do { const float e0_ = __builtin_amdgcn_exp2f(PX[R]), e1_ = __builtin_amdgcn_exp2f(PX[(R) + 1]); ps += e0_; ps += e1_; PWN[(J) >> 2][(J) & 3] = cvtpk(e0_, e1_); } while (0)
; __device__ __forceinline__ void attn_unit_a(FLAS unsigned char* lds, const Unit u) {
;     ...
;         for (int g = 8; g < 16; ++g) { FA_PVM(g); FA_EXP2(g - 8, pC0, 2 * (g - 8));
;             if (g == 12) { kf[0] = FA_KF(0, 0); kf[1] = FA_KF(0, 1); kf[2] = FA_KF(1, 0); kf[3] = FA_KF(1, 1); }
;             FA_SB(); }
;         float cbN; bool ziN; const int inx = (i + 1 < NT) ? i + 1 : NT - 1;
;         FA_BIAS(inx, pN0, pN1, cbN, ziN);
;         FA_SB();
;         if (ziN) { pN0 = __builtin_amdgcn_mfma_f32_32x32x16_bf16(kf[0], qr[0], z16, 0, 0, 0); FA_EXP2(8, pC1, 0); FA_SB(); pN1 = __builtin_amdgcn_mfma_f32_32x32x16_bf16(kf[1], qr[0], z16, 0, 0, 0); }
;         else { pN0 = __builtin_amdgcn_mfma_f32_32x32x16_bf16(kf[0], qr[0], pN0, 0, 0, 0); FA_EXP2(8, pC1, 0); FA_SB(); pN1 = __builtin_amdgcn_mfma_f32_32x32x16_bf16(kf[1], qr[0], pN1, 0, 0, 0); }
;         kf[0] = FA_KF(2, 0); kf[1] = FA_KF(2, 1); FA_EXP2(9, pC1, 2); FA_SB();
;         pN0 = __builtin_amdgcn_mfma_f32_32x32x16_bf16(kf[2], qr[1], pN0, 0, 0, 0); FA_EXP2(10, pC1, 4); FA_SB();
;         pN1 = __builtin_amdgcn_mfma_f32_32x32x16_bf16(kf[3], qr[1], pN1, 0, 0, 0); kf[2] = FA_KF(3, 0); kf[3] = FA_KF(3, 1); FA_EXP2(11, pC1, 6); FA_SB();
;         pN0 = __builtin_amdgcn_mfma_f32_32x32x16_bf16(kf[0], qr[2], pN0, 0, 0, 0); FA_EXP2(12, pC1, 8); FA_SB();
;         pN1 = __builtin_amdgcn_mfma_f32_32x32x16_bf16(kf[1], qr[2], pN1, 0, 0, 0); FA_EXP2(13, pC1, 10); FA_SB();
;         pN0 = __builtin_amdgcn_mfma_f32_32x32x16_bf16(kf[2], qr[3], pN0, 0, 0, 0); FA_EXP2(14, pC1, 12); FA_SB();
;         pN1 = __builtin_amdgcn_mfma_f32_32x32x16_bf16(kf[3], qr[3], pN1, 0, 0, 0); FA_EXP2(15, pC1, 14); FA_SB();
.LBB0_442:
	s_waitcnt lgkmcnt(2)
	v_mfma_f32_32x32x16_bf16 v[48:63], v[136:139], v[192:195], v[48:63]
	ds_read_b128 v[136:139], v200 offset:30272
	v_exp_f32_e32 v96, v96
	v_exp_f32_e32 v97, v97
	s_waitcnt lgkmcnt(2)
	v_mfma_f32_32x32x16_bf16 v[32:47], v[128:131], v[192:195], v[32:47]
	ds_read_b128 v[128:131], v200 offset:16480
	v_exp_f32_e32 v98, v98
	v_exp_f32_e32 v99, v99
	v_add_f32_e32 v212, v96, v212
	v_add_f32_e32 v212, v97, v212
	s_waitcnt lgkmcnt(2)
	v_mfma_f32_32x32x16_bf16 v[16:31], v[132:135], v[192:195], v[16:31]
	ds_read_b128 v[132:135], v200 offset:21088
	v_exp_f32_e32 v100, v100
	v_exp_f32_e32 v101, v101
	v_add_f32_e32 v212, v98, v212
	v_add_f32_e32 v212, v99, v212
	s_waitcnt lgkmcnt(2)
	v_mfma_f32_32x32x16_bf16 v[0:15], v[136:139], v[192:195], v[0:15]
	ds_read_b128 v[136:139], v200 offset:25696
	v_exp_f32_e32 v102, v102
	v_exp_f32_e32 v103, v103
	v_add_f32_e32 v212, v100, v212
	v_add_f32_e32 v212, v101, v212
	s_waitcnt lgkmcnt(2)
	v_mfma_f32_32x32x16_bf16 v[48:63], v[128:131], v[188:191], v[48:63]
	ds_read_b128 v[128:131], v200 offset:30304
	ds_read_b128 v[204:207], v247 offset:8192
	ds_read_b128 v[200:203], v247 offset:8704
	ds_read_b128 v[196:199], v248 offset:8192
	ds_read_b128 v[192:195], v248 offset:8704
	v_exp_f32_e32 v104, v104
	v_exp_f32_e32 v105, v105
	v_add_f32_e32 v212, v102, v212
	v_add_f32_e32 v212, v103, v212
	s_waitcnt lgkmcnt(6)
	v_mfma_f32_32x32x16_bf16 v[32:47], v[132:135], v[188:191], v[32:47]
	v_exp_f32_e32 v106, v106
	v_exp_f32_e32 v107, v107
	v_add_f32_e32 v212, v104, v212
	v_add_f32_e32 v212, v105, v212
	s_waitcnt lgkmcnt(5)
	v_mfma_f32_32x32x16_bf16 v[16:31], v[136:139], v[188:191], v[16:31]
	v_exp_f32_e32 v108, v108
	v_exp_f32_e32 v109, v109
	v_add_f32_e32 v212, v106, v212
	v_add_f32_e32 v212, v107, v212
	s_waitcnt lgkmcnt(4)
	v_mfma_f32_32x32x16_bf16 v[0:15], v[128:131], v[188:191], v[0:15]
	v_exp_f32_e32 v110, v110
	v_exp_f32_e32 v111, v111
	v_add_f32_e32 v212, v108, v212
	v_add_f32_e32 v212, v109, v212
	s_sub_i32 s12, s48, 31
	s_cmpk_lt_i32 s12, 0x22f
	s_cselect_b32 s98, s100, s101
	s_cselect_b32 s99, 1, 0
	s_cmpk_gt_i32 s48, 0xfd92
	s_cselect_b32 s99, s99, 0
	s_cmp_lg_u32 s99, 0
	s_cbranch_scc1 .Lgather_e
	v_sub_f32_e32 v142, s98, v211
	v_cmp_neq_f32_e32 vcc, v142, v144
	s_cbranch_vccnz .Lz_upd_e
.Lz_go_e:
	s_waitcnt lgkmcnt(0)
	v_mfma_f32_32x32x16_bf16 v[64:79], v[204:207], v[160:163], v[144:159]
	v_exp_f32_e32 v112, v112
	v_exp_f32_e32 v113, v113
	v_add_f32_e32 v212, v110, v212
	v_add_f32_e32 v212, v111, v212
	v_mfma_f32_32x32x16_bf16 v[80:95], v[200:203], v[160:163], v[144:159]
	v_exp_f32_e32 v114, v114
	v_exp_f32_e32 v115, v115
.Lk2_e:
	ds_read_b128 v[128:131], v249 offset:8192
	ds_read_b128 v[132:135], v249 offset:8704
	s_add_i32 s34, s19, 2
	v_mfma_f32_32x32x16_bf16 v[64:79], v[196:199], v[164:167], v[64:79]
	v_exp_f32_e32 v116, v116
	v_exp_f32_e32 v117, v117
	v_mfma_f32_32x32x16_bf16 v[80:95], v[192:195], v[164:167], v[80:95]
	ds_read_b128 v[136:139], v250 offset:8192
	ds_read_b128 v[140:143], v250 offset:8704
	s_and_b32 s0, s34, 2
	s_mulk_i32 s0, 0x4800
	v_add_u32_e32 v188, s0, v245
	v_add_u32_e32 v189, 0x4000, v188
	v_add_u32_e32 v188, 0x6000, v188
	s_waitcnt vmcnt(2)
	ds_write_b128 v225, v[176:179]
	s_waitcnt vmcnt(1)
	ds_write2_b64 v189, v[180:181], v[182:183] offset1:2
	s_waitcnt vmcnt(0)
	ds_write2_b64 v188, v[184:185], v[186:187] offset0:128 offset1:130
	v_exp_f32_e32 v118, v118
	v_exp_f32_e32 v119, v119
	s_and_b32 s0, s19, 2
	s_mulk_i32 s0, 0x4800
	v_add_u32_e32 v201, s0, v251
	s_waitcnt lgkmcnt(6)
	v_mfma_f32_32x32x16_bf16 v[64:79], v[128:131], v[168:171], v[64:79]
	ds_read_b128 v[128:131], v201 offset:16384
	v_exp_f32_e32 v120, v120
	v_exp_f32_e32 v121, v121
	s_waitcnt lgkmcnt(6)
	v_mfma_f32_32x32x16_bf16 v[80:95], v[132:135], v[168:171], v[80:95]
	ds_read_b128 v[132:135], v201 offset:20992
	v_exp_f32_e32 v122, v122
	v_exp_f32_e32 v123, v123
	s_waitcnt lgkmcnt(6)
	v_mfma_f32_32x32x16_bf16 v[64:79], v[136:139], v[172:175], v[64:79]
	ds_read_b128 v[136:139], v201 offset:25600
	v_exp_f32_e32 v124, v124
	v_exp_f32_e32 v125, v125
	s_waitcnt lgkmcnt(6)
	v_mfma_f32_32x32x16_bf16 v[80:95], v[140:143], v[172:175], v[80:95]
	v_exp_f32_e32 v126, v126
	v_exp_f32_e32 v127, v127
	v_cvt_pk_bf16_f32 v140, v96, v97
	v_cvt_pk_bf16_f32 v141, v98, v99
	v_cvt_pk_bf16_f32 v142, v100, v101
	v_cvt_pk_bf16_f32 v143, v102, v103
.LBB0_456:
	s_and_b64 vcc, exec, s[20:21]
	s_waitcnt lgkmcnt(0)
	s_barrier
	s_cbranch_vccnz .Lpend_e

; #define FLAS __attribute__((address_space(3)))
; __device__ __forceinline__ void attn_unit_a(FLAS unsigned char* lds, const Unit u) {
;     ...
;         for (int g = 8; g < 16; ++g) { FA_PVM(g); FA_EXP2(g - 8, pC0, 2 * (g - 8));
;             if (g == 12) { kf[0] = FA_KF(0, 0); kf[1] = FA_KF(0, 1); kf[2] = FA_KF(1, 0); kf[3] = FA_KF(1, 1); }
;             FA_SB(); }
;         float cbN; bool ziN; const int inx = (i + 1 < NT) ? i + 1 : NT - 1;
;         FA_BIAS(inx, pN0, pN1, cbN, ziN);
;         FA_SB();
;         if (ziN) { pN0 = __builtin_amdgcn_mfma_f32_32x32x16_bf16(kf[0], qr[0], z16, 0, 0, 0); FA_EXP2(8, pC1, 0); FA_SB(); pN1 = __builtin_amdgcn_mfma_f32_32x32x16_bf16(kf[1], qr[0], z16, 0, 0, 0); }
;         else { pN0 = __builtin_amdgcn_mfma_f32_32x32x16_bf16(kf[0], qr[0], pN0, 0, 0, 0); FA_EXP2(8, pC1, 0); FA_SB(); pN1 = __builtin_amdgcn_mfma_f32_32x32x16_bf16(kf[1], qr[0], pN1, 0, 0, 0); }
;         kf[0] = FA_KF(2, 0); kf[1] = FA_KF(2, 1); FA_EXP2(9, pC1, 2); FA_SB();
;         pN0 = __builtin_amdgcn_mfma_f32_32x32x16_bf16(kf[2], qr[1], pN0, 0, 0, 0); FA_EXP2(10, pC1, 4); FA_SB();
;         pN1 = __builtin_amdgcn_mfma_f32_32x32x16_bf16(kf[3], qr[1], pN1, 0, 0, 0); kf[2] = FA_KF(3, 0); kf[3] = FA_KF(3, 1); FA_EXP2(11, pC1, 6); FA_SB();
;         pN0 = __builtin_amdgcn_mfma_f32_32x32x16_bf16(kf[0], qr[2], pN0, 0, 0, 0); FA_EXP2(12, pC1, 8); FA_SB();
;         pN1 = __builtin_amdgcn_mfma_f32_32x32x16_bf16(kf[1], qr[2], pN1, 0, 0, 0); FA_EXP2(13, pC1, 10); FA_SB();
;         pN0 = __builtin_amdgcn_mfma_f32_32x32x16_bf16(kf[2], qr[3], pN0, 0, 0, 0); FA_EXP2(14, pC1, 12); FA_SB();
;         pN1 = __builtin_amdgcn_mfma_f32_32x32x16_bf16(kf[3], qr[3], pN1, 0, 0, 0); FA_EXP2(15, pC1, 14); FA_SB();
;     ...
;         lsum += ps; cbC = cbN;
;         if (i + 2 < NT) { *(FLAS u32x4*)(lds + LA_K + (i & 1) * KBUF + kdst) = kreg;
; #pragma unroll
;             for (int j = 0; j < 2; ++j) { *(FLAS u32x2*)(lds + LA_V + ((i + 2) & 3) * VBUF + vdst + j * 64 * VPITCH) = (u32x2){vreg[j].x, vreg[j].y}; *(FLAS u32x2*)(lds + LA_V + ((i + 2) & 3) * VBUF + vdst + j * 64 * VPITCH + 16) = (u32x2){vreg[j].z, vreg[j].w}; } }
;         __syncthreads();
;     };
;     for (int i = 0; i < NT; i += 2) { step(i, pa0, pa1, pb0, pb1, pwa, pwb); if (i + 1 < NT) step(i + 1, pb0, pb1, pa0, pa1, pwb, pwa); }
;     if (pend) {
; #pragma unroll
;         for (int d = 0; d < NDB; ++d) o[d] = o[d] * fpend; }
.LBB0_462:
	s_waitcnt lgkmcnt(2)
	v_mfma_f32_32x32x16_bf16 v[48:63], v[136:139], v[140:143], v[48:63]
	ds_read_b128 v[136:139], v201 offset:30272
	v_exp_f32_e32 v64, v64
	v_exp_f32_e32 v65, v65
	v_cvt_pk_bf16_f32 v232, v120, v121
	v_cvt_pk_bf16_f32 v233, v122, v123
	s_waitcnt lgkmcnt(2)
	v_mfma_f32_32x32x16_bf16 v[32:47], v[128:131], v[140:143], v[32:47]
	ds_read_b128 v[128:131], v201 offset:16480
	v_exp_f32_e32 v66, v66
	v_exp_f32_e32 v67, v67
	v_add_f32_e32 v212, v64, v212
	v_add_f32_e32 v212, v65, v212
	v_cvt_pk_bf16_f32 v234, v124, v125
	v_cvt_pk_bf16_f32 v235, v126, v127
	s_waitcnt lgkmcnt(2)
	v_mfma_f32_32x32x16_bf16 v[16:31], v[132:135], v[140:143], v[16:31]
	ds_read_b128 v[132:135], v201 offset:21088
	v_exp_f32_e32 v68, v68
	v_exp_f32_e32 v69, v69
	v_add_f32_e32 v212, v66, v212
	v_add_f32_e32 v212, v67, v212
	s_waitcnt lgkmcnt(2)
	v_mfma_f32_32x32x16_bf16 v[0:15], v[136:139], v[140:143], v[0:15]
	ds_read_b128 v[136:139], v201 offset:25696
	v_exp_f32_e32 v70, v70
	v_exp_f32_e32 v71, v71
	v_add_f32_e32 v212, v68, v212
	v_add_f32_e32 v212, v69, v212
	s_waitcnt lgkmcnt(2)
	v_mfma_f32_32x32x16_bf16 v[48:63], v[128:131], v[232:235], v[48:63]
	ds_read_b128 v[128:131], v201 offset:30304
	ds_read_b128 v[200:203], v247
	ds_read_b128 v[196:199], v247 offset:512
	ds_read_b128 v[192:195], v248
	ds_read_b128 v[188:191], v248 offset:512
	v_exp_f32_e32 v72, v72
	v_exp_f32_e32 v73, v73
	v_add_f32_e32 v212, v70, v212
	v_add_f32_e32 v212, v71, v212
	s_waitcnt lgkmcnt(6)
	v_mfma_f32_32x32x16_bf16 v[32:47], v[132:135], v[232:235], v[32:47]
	v_exp_f32_e32 v74, v74
	v_exp_f32_e32 v75, v75
	v_add_f32_e32 v212, v72, v212
	v_add_f32_e32 v212, v73, v212
	s_waitcnt lgkmcnt(5)
	v_mfma_f32_32x32x16_bf16 v[16:31], v[136:139], v[232:235], v[16:31]
	v_exp_f32_e32 v76, v76
	v_exp_f32_e32 v77, v77
	v_add_f32_e32 v212, v74, v212
	v_add_f32_e32 v212, v75, v212
	s_waitcnt lgkmcnt(4)
	v_mfma_f32_32x32x16_bf16 v[0:15], v[128:131], v[232:235], v[0:15]
	v_exp_f32_e32 v78, v78
	v_exp_f32_e32 v79, v79
	v_add_f32_e32 v212, v76, v212
	v_add_f32_e32 v212, v77, v212
	s_min_u32 s12, s34, 0x7f
	s_lshl_b32 s12, s12, 6
	s_sub_i32 s14, s12, s47
	s_sub_i32 s15, s14, 31
	s_cmpk_lt_i32 s15, 0x22f
	s_cselect_b32 s98, s100, s101
	s_cselect_b32 s99, 1, 0
	s_cmpk_gt_i32 s14, 0xfd92
	s_cselect_b32 s99, s99, 0
	s_cmp_lg_u32 s99, 0
	s_cbranch_scc1 .Lgather_o
	v_sub_f32_e32 v126, s98, v211
	v_cmp_neq_f32_e32 vcc, v126, v144
	s_cbranch_vccnz .Lz_upd_o
.Lz_go_o:
	s_waitcnt lgkmcnt(0)
	v_mfma_f32_32x32x16_bf16 v[96:111], v[200:203], v[160:163], v[144:159]
	v_exp_f32_e32 v80, v80
	v_exp_f32_e32 v81, v81
	v_add_f32_e32 v212, v78, v212
	v_add_f32_e32 v212, v79, v212
	v_mfma_f32_32x32x16_bf16 v[112:127], v[196:199], v[160:163], v[144:159]
	v_exp_f32_e32 v82, v82
	v_exp_f32_e32 v83, v83
.Lk2_o:
	ds_read_b128 v[128:131], v249
	ds_read_b128 v[132:135], v249 offset:512
	v_mfma_f32_32x32x16_bf16 v[96:111], v[192:195], v[164:167], v[96:111]
	v_exp_f32_e32 v84, v84
	v_exp_f32_e32 v85, v85
	v_mfma_f32_32x32x16_bf16 v[112:127], v[188:191], v[164:167], v[112:127]
	ds_read_b128 v[136:139], v250
	ds_read_b128 v[140:143], v250 offset:512
	v_add_u32_e32 v204, s18, v245
	v_add_u32_e32 v205, 0x4000, v204
	v_add_u32_e32 v204, 0x6000, v204
	s_waitcnt vmcnt(2)
	ds_write_b128 v225, v[176:179] offset:8192
	s_waitcnt vmcnt(1)
	ds_write2_b64 v205, v[180:181], v[182:183] offset1:2
	s_waitcnt vmcnt(0)
	ds_write2_b64 v204, v[184:185], v[186:187] offset0:128 offset1:130
	v_exp_f32_e32 v86, v86
	v_exp_f32_e32 v87, v87
	s_add_i32 s12, s34, -1
	s_and_b32 s18, s12, 3
	s_mulk_i32 s18, 0x4800
	v_add_u32_e32 v200, s18, v251
	s_waitcnt lgkmcnt(6)
	v_mfma_f32_32x32x16_bf16 v[96:111], v[128:131], v[168:171], v[96:111]
	ds_read_b128 v[128:131], v200 offset:16384
	v_exp_f32_e32 v88, v88
	v_exp_f32_e32 v89, v89
	s_waitcnt lgkmcnt(6)
	v_mfma_f32_32x32x16_bf16 v[112:127], v[132:135], v[168:171], v[112:127]
	ds_read_b128 v[132:135], v200 offset:20992
	v_exp_f32_e32 v90, v90
	v_exp_f32_e32 v91, v91
	s_waitcnt lgkmcnt(6)
	v_mfma_f32_32x32x16_bf16 v[96:111], v[136:139], v[172:175], v[96:111]
	ds_read_b128 v[136:139], v200 offset:25600
	v_exp_f32_e32 v92, v92
	v_exp_f32_e32 v93, v93
	s_waitcnt lgkmcnt(6)
	v_mfma_f32_32x32x16_bf16 v[112:127], v[140:143], v[172:175], v[112:127]
	v_exp_f32_e32 v94, v94
	v_exp_f32_e32 v95, v95
.LBB0_476:
	s_mov_b64 s[14:15], 0x100
	v_lshl_add_u64 v[228:229], v[228:229], 0, s[14:15]
	s_mov_b64 s[14:15], 0x60000
	v_cvt_pk_bf16_f32 v206, v68, v69
	v_cvt_pk_bf16_f32 v207, v70, v71
	s_addk_i32 s48, 0x80
	s_addk_i32 s49, 0x200
	v_lshl_add_u64 v[230:231], v[230:231], 0, s[14:15]
	s_mov_b64 s[24:25], 0
	s_and_b64 vcc, exec, s[4:5]
	v_cvt_pk_bf16_f32 v204, v64, v65
	v_cvt_pk_bf16_f32 v205, v66, v67
	s_waitcnt lgkmcnt(0)
	s_barrier
	s_cbranch_vccnz .Lexit_a
	s_mov_b32 s19, s34
	s_and_b64 vcc, exec, s[0:1]
	s_cbranch_vccnz .LBB0_434
	s_branch .LBB0_435
.Lexit_a:
	s_setprio 0
	s_andn2_b64 vcc, exec, s[0:1]
	s_cbranch_vccnz .LBB0_479
	v_pk_mul_f32 v[62:63], v[62:63], v[226:227] op_sel_hi:[1,0]
	v_pk_mul_f32 v[60:61], v[60:61], v[226:227] op_sel_hi:[1,0]
	v_pk_mul_f32 v[58:59], v[58:59], v[226:227] op_sel_hi:[1,0]
	v_pk_mul_f32 v[56:57], v[56:57], v[226:227] op_sel_hi:[1,0]
	v_pk_mul_f32 v[54:55], v[54:55], v[226:227] op_sel_hi:[1,0]
	v_pk_mul_f32 v[52:53], v[52:53], v[226:227] op_sel_hi:[1,0]
	v_pk_mul_f32 v[50:51], v[50:51], v[226:227] op_sel_hi:[1,0]
	v_pk_mul_f32 v[48:49], v[48:49], v[226:227] op_sel_hi:[1,0]
	v_pk_mul_f32 v[46:47], v[46:47], v[226:227] op_sel_hi:[1,0]
	v_pk_mul_f32 v[44:45], v[44:45], v[226:227] op_sel_hi:[1,0]
	v_pk_mul_f32 v[42:43], v[42:43], v[226:227] op_sel_hi:[1,0]
	v_pk_mul_f32 v[40:41], v[40:41], v[226:227] op_sel_hi:[1,0]
	v_pk_mul_f32 v[38:39], v[38:39], v[226:227] op_sel_hi:[1,0]
	v_pk_mul_f32 v[36:37], v[36:37], v[226:227] op_sel_hi:[1,0]
	v_pk_mul_f32 v[34:35], v[34:35], v[226:227] op_sel_hi:[1,0]
	v_pk_mul_f32 v[32:33], v[32:33], v[226:227] op_sel_hi:[1,0]
	v_pk_mul_f32 v[30:31], v[30:31], v[226:227] op_sel_hi:[1,0]
	v_pk_mul_f32 v[28:29], v[28:29], v[226:227] op_sel_hi:[1,0]
	v_pk_mul_f32 v[26:27], v[26:27], v[226:227] op_sel_hi:[1,0]
	v_pk_mul_f32 v[24:25], v[24:25], v[226:227] op_sel_hi:[1,0]
	v_pk_mul_f32 v[22:23], v[22:23], v[226:227] op_sel_hi:[1,0]
	v_pk_mul_f32 v[20:21], v[20:21], v[226:227] op_sel_hi:[1,0]
	v_pk_mul_f32 v[18:19], v[18:19], v[226:227] op_sel_hi:[1,0]
	v_pk_mul_f32 v[16:17], v[16:17], v[226:227] op_sel_hi:[1,0]
	v_pk_mul_f32 v[14:15], v[14:15], v[226:227] op_sel_hi:[1,0]
	v_pk_mul_f32 v[12:13], v[12:13], v[226:227] op_sel_hi:[1,0]
	v_pk_mul_f32 v[10:11], v[10:11], v[226:227] op_sel_hi:[1,0]
	v_pk_mul_f32 v[8:9], v[8:9], v[226:227] op_sel_hi:[1,0]
	v_pk_mul_f32 v[6:7], v[6:7], v[226:227] op_sel_hi:[1,0]
	v_pk_mul_f32 v[4:5], v[4:5], v[226:227] op_sel_hi:[1,0]
	v_pk_mul_f32 v[2:3], v[2:3], v[226:227] op_sel_hi:[1,0]
	v_pk_mul_f32 v[0:1], v[0:1], v[226:227] op_sel_hi:[1,0]
